# GEMM K-loops variant E: fragment ds_reads interleaved into the preceding MFMA group (no read bursts), ds_write+load pairs from MFMA 20, exact counted waits
# speedup vs baseline: 1.0330x; 1.0124x over previous
; #define MFMA32(a, b, c) __builtin_amdgcn_mfma_f32_32x32x16_bf16((a), (b), (c), 0, 0, 0)
; #define G_LOAD(KT) do { const int k0_ = (KT) << 6; _Pragma("unroll") for (int p = 0; p < 4; ++p) { \
;     ra[p] = *(const u32x4*)(ap + (size_t)(64 * p) * lda + k0_); rb[p] = *(const u32x4*)(bp + (size_t)(64 * p) * ldb + k0_); } } while (0)
; template <bool SWAP, bool SSQ, bool ZERO = true>
; DI void gemm_main(const u16* __restrict__ A, int lda, const u16* __restrict__ Bt, int ldb, int K, char* lds,
;                   f32x16 (&acc)[4][2], float* rs_lds) {
;     ...
;   for (int kt = 0; kt < nk; ++kt) {
;     const int st = (kt & 1) * 2 * G_TILE;
;     {
;       bf16x8 fa[2][4], fb[2][2];
; #pragma unroll
;       for (int i = 0; i < 4; ++i) fa[0][i] = *(const bf16x8*)(abase + st + i * 32 * GS);
; #pragma unroll
;       for (int i = 0; i < 2; ++i) fb[0][i] = *(const bf16x8*)(bbase + st + i * 32 * GS);
; #pragma unroll
;       for (int ks = 0; ks < 4; ++ks) {
;         if (ks + 1 < 4) {
; #pragma unroll
;           for (int i = 0; i < 4; ++i) fa[(ks + 1) & 1][i] = *(const bf16x8*)(abase + st + i * 32 * GS + (ks + 1) * 32);
; #pragma unroll
;           for (int i = 0; i < 2; ++i) fb[(ks + 1) & 1][i] = *(const bf16x8*)(bbase + st + i * 32 * GS + (ks + 1) * 32);
;         }
;         __builtin_amdgcn_sched_barrier(0);
;         __builtin_amdgcn_s_setprio(1);
; #pragma unroll
;         for (int mt = 0; mt < 4; ++mt)
; #pragma unroll
;           for (int nt = 0; nt < 2; ++nt)
;             acc[mt][nt] = SWAP ? MFMA32(fb[ks & 1][nt], fa[ks & 1][mt], acc[mt][nt]) : MFMA32(fa[ks & 1][mt], fb[ks & 1][nt], acc[mt][nt]);
;         __builtin_amdgcn_s_setprio(0);
;         __builtin_amdgcn_sched_barrier(0);
;       }
;     }
;     if (kt + 1 < nk) G_WRITE((kt + 1) & 1);
;     if (kt + 2 < nk) G_LOAD(kt + 2);
;     __syncthreads();
;   }
.LBB0_92:
	s_cmp_gt_u32 s52, 29
	s_cbranch_scc1 .Lg92_tail
	ds_read_b128 v[204:207], v165 offset:36864
	ds_read_b128 v[172:175], v0
	ds_read_b128 v[212:215], v165 offset:41472
	ds_read_b128 v[180:183], v0 offset:4608
	ds_read_b128 v[188:191], v0 offset:9216
	ds_read_b128 v[196:199], v0 offset:13824
	s_setprio 1
	s_waitcnt lgkmcnt(4)
	v_mfma_f32_32x32x16_bf16 v[114:129], v[204:207], v[172:175], v[114:129]
	ds_read_b128 v[208:211], v165 offset:36896
	s_waitcnt lgkmcnt(4)
	v_mfma_f32_32x32x16_bf16 v[98:113], v[212:215], v[172:175], v[98:113]
	ds_read_b128 v[176:179], v0 offset:32
	ds_read_b128 v[172:175], v0 offset:64
	s_waitcnt lgkmcnt(5)
	v_mfma_f32_32x32x16_bf16 v[82:97], v[204:207], v[180:183], v[82:97]
	ds_read_b128 v[216:219], v165 offset:41504
	v_mfma_f32_32x32x16_bf16 v[66:81], v[212:215], v[180:183], v[66:81]
	ds_read_b128 v[184:187], v0 offset:4640
	ds_read_b128 v[180:183], v0 offset:4672
	s_waitcnt lgkmcnt(7)
	v_mfma_f32_32x32x16_bf16 v[50:65], v[204:207], v[188:191], v[50:65]
	ds_read_b128 v[192:195], v0 offset:9248
	v_mfma_f32_32x32x16_bf16 v[34:49], v[212:215], v[188:191], v[34:49]
	ds_read_b128 v[200:203], v0 offset:13856
	ds_read_b128 v[188:191], v0 offset:9280
	s_waitcnt lgkmcnt(9)
	v_mfma_f32_32x32x16_bf16 v[18:33], v[204:207], v[196:199], v[18:33]
	ds_read_b128 v[204:207], v165 offset:36928
	v_mfma_f32_32x32x16_bf16 v[2:17], v[212:215], v[196:199], v[2:17]
	ds_read_b128 v[212:215], v165 offset:41536
	ds_read_b128 v[196:199], v0 offset:13888
	s_setprio 0
	s_setprio 1
	s_waitcnt lgkmcnt(10)
	v_mfma_f32_32x32x16_bf16 v[114:129], v[208:211], v[176:179], v[114:129]
	s_waitcnt lgkmcnt(8)
	v_mfma_f32_32x32x16_bf16 v[98:113], v[216:219], v[176:179], v[98:113]
	ds_read_b128 v[176:179], v0 offset:96
	s_waitcnt lgkmcnt(8)
	v_mfma_f32_32x32x16_bf16 v[82:97], v[208:211], v[184:187], v[82:97]
	v_mfma_f32_32x32x16_bf16 v[66:81], v[216:219], v[184:187], v[66:81]
	ds_read_b128 v[184:187], v0 offset:4704
	s_waitcnt lgkmcnt(7)
	v_mfma_f32_32x32x16_bf16 v[50:65], v[208:211], v[192:195], v[50:65]
	v_mfma_f32_32x32x16_bf16 v[34:49], v[216:219], v[192:195], v[34:49]
	ds_read_b128 v[192:195], v0 offset:9312
	s_waitcnt lgkmcnt(7)
	v_mfma_f32_32x32x16_bf16 v[18:33], v[208:211], v[200:203], v[18:33]
	ds_read_b128 v[208:211], v165 offset:36960
	v_mfma_f32_32x32x16_bf16 v[2:17], v[216:219], v[200:203], v[2:17]
	ds_read_b128 v[216:219], v165 offset:41568
	ds_read_b128 v[200:203], v0 offset:13920
	s_setprio 0
	s_setprio 1
	s_waitcnt lgkmcnt(8)
	v_mfma_f32_32x32x16_bf16 v[114:129], v[204:207], v[172:175], v[114:129]
	s_waitcnt lgkmcnt(7)
	v_mfma_f32_32x32x16_bf16 v[98:113], v[212:215], v[172:175], v[98:113]
	v_mfma_f32_32x32x16_bf16 v[82:97], v[204:207], v[180:183], v[82:97]
	v_mfma_f32_32x32x16_bf16 v[66:81], v[212:215], v[180:183], v[66:81]
	s_and_b32 s62, s53, 2
	s_mul_i32 s62, s62, 0x9000
	v_add_u32_e32 v240, s62, v162
	v_lshl_add_u64 v[220:221], v[168:169], 0, s[86:87]
	v_lshl_add_u64 v[234:235], v[166:167], 0, s[86:87]
	v_mfma_f32_32x32x16_bf16 v[50:65], v[204:207], v[188:191], v[50:65]
	s_waitcnt vmcnt(7)
	ds_write_b128 v240, v[130:133]
	global_load_dwordx4 v[130:133], v[220:221], off offset:256
	v_add_co_u32_e32 v220, vcc, 0x40000, v220
	v_mfma_f32_32x32x16_bf16 v[34:49], v[212:215], v[188:191], v[34:49]
	s_waitcnt vmcnt(7)
	ds_write_b128 v240, v[134:137] offset:36864
	v_addc_co_u32_e32 v221, vcc, 0, v221, vcc
	global_load_dwordx4 v[134:137], v[234:235], off offset:256
	v_add_co_u32_e32 v234, vcc, 0x40000, v234
	s_waitcnt lgkmcnt(8)
	v_mfma_f32_32x32x16_bf16 v[18:33], v[204:207], v[196:199], v[18:33]
	s_waitcnt vmcnt(7)
	ds_write_b128 v240, v[138:141] offset:9216
	v_addc_co_u32_e32 v235, vcc, 0, v235, vcc
	global_load_dwordx4 v[138:141], v[220:221], off offset:256
	v_add_co_u32_e32 v220, vcc, 0x40000, v220
	v_mfma_f32_32x32x16_bf16 v[2:17], v[212:215], v[196:199], v[2:17]
	s_waitcnt vmcnt(7)
	ds_write_b128 v240, v[142:145] offset:46080
	v_addc_co_u32_e32 v221, vcc, 0, v221, vcc
	global_load_dwordx4 v[142:145], v[234:235], off offset:256
	v_add_co_u32_e32 v234, vcc, 0x40000, v234
	s_setprio 0
	s_setprio 1
	s_waitcnt lgkmcnt(6)
	v_mfma_f32_32x32x16_bf16 v[114:129], v[208:211], v[176:179], v[114:129]
	s_waitcnt vmcnt(7)
	ds_write_b128 v240, v[146:149] offset:18432
	v_addc_co_u32_e32 v235, vcc, 0, v235, vcc
	global_load_dwordx4 v[146:149], v[220:221], off offset:256
	v_add_co_u32_e32 v220, vcc, 0x40000, v220
	s_waitcnt lgkmcnt(6)
	v_mfma_f32_32x32x16_bf16 v[98:113], v[216:219], v[176:179], v[98:113]
	s_waitcnt vmcnt(7)
	ds_write_b128 v240, v[150:153] offset:55296
	v_addc_co_u32_e32 v221, vcc, 0, v221, vcc
	global_load_dwordx4 v[150:153], v[234:235], off offset:256
	v_add_co_u32_e32 v234, vcc, 0x40000, v234
	v_mfma_f32_32x32x16_bf16 v[82:97], v[208:211], v[184:187], v[82:97]
	s_waitcnt vmcnt(7)
	ds_write_b128 v240, v[154:157] offset:27648
	v_addc_co_u32_e32 v235, vcc, 0, v235, vcc
	global_load_dwordx4 v[154:157], v[220:221], off offset:256
	v_mfma_f32_32x32x16_bf16 v[66:81], v[216:219], v[184:187], v[66:81]
	s_waitcnt vmcnt(7)
	ds_write_b128 v240, v[158:161] offset:64512
	global_load_dwordx4 v[158:161], v[234:235], off offset:256
	v_mfma_f32_32x32x16_bf16 v[50:65], v[208:211], v[192:195], v[50:65]
	v_mfma_f32_32x32x16_bf16 v[34:49], v[216:219], v[192:195], v[34:49]
	s_waitcnt lgkmcnt(8)
	v_mfma_f32_32x32x16_bf16 v[18:33], v[208:211], v[200:203], v[18:33]
	v_mfma_f32_32x32x16_bf16 v[2:17], v[216:219], v[200:203], v[2:17]
	s_setprio 0
	s_branch .LBB0_91
; #define MFMA32(a, b, c) __builtin_amdgcn_mfma_f32_32x32x16_bf16((a), (b), (c), 0, 0, 0)
; #define G_LOAD(KT) do { const int k0_ = (KT) << 6; _Pragma("unroll") for (int p = 0; p < 4; ++p) { \
;     ra[p] = *(const u32x4*)(ap + (size_t)(64 * p) * lda + k0_); rb[p] = *(const u32x4*)(bp + (size_t)(64 * p) * ldb + k0_); } } while (0)
; template <bool SWAP, bool SSQ, bool ZERO = true>
; DI void gemm_main(const u16* __restrict__ A, int lda, const u16* __restrict__ Bt, int ldb, int K, char* lds,
;                   f32x16 (&acc)[4][2], float* rs_lds) {
;     ...
;   for (int kt = 0; kt < nk; ++kt) {
;     const int st = (kt & 1) * 2 * G_TILE;
;     {
;       bf16x8 fa[2][4], fb[2][2];
; #pragma unroll
;       for (int i = 0; i < 4; ++i) fa[0][i] = *(const bf16x8*)(abase + st + i * 32 * GS);
; #pragma unroll
;       for (int i = 0; i < 2; ++i) fb[0][i] = *(const bf16x8*)(bbase + st + i * 32 * GS);
; #pragma unroll
;       for (int ks = 0; ks < 4; ++ks) {
;         if (ks + 1 < 4) {
; #pragma unroll
;           for (int i = 0; i < 4; ++i) fa[(ks + 1) & 1][i] = *(const bf16x8*)(abase + st + i * 32 * GS + (ks + 1) * 32);
; #pragma unroll
;           for (int i = 0; i < 2; ++i) fb[(ks + 1) & 1][i] = *(const bf16x8*)(bbase + st + i * 32 * GS + (ks + 1) * 32);
;         }
;         __builtin_amdgcn_sched_barrier(0);
;         __builtin_amdgcn_s_setprio(1);
; #pragma unroll
;         for (int mt = 0; mt < 4; ++mt)
; #pragma unroll
;           for (int nt = 0; nt < 2; ++nt)
;             acc[mt][nt] = SWAP ? MFMA32(fb[ks & 1][nt], fa[ks & 1][mt], acc[mt][nt]) : MFMA32(fa[ks & 1][mt], fb[ks & 1][nt], acc[mt][nt]);
;         __builtin_amdgcn_s_setprio(0);
;         __builtin_amdgcn_sched_barrier(0);
;       }
;     }
;     if (kt + 1 < nk) G_WRITE((kt + 1) & 1);
;     if (kt + 2 < nk) G_LOAD(kt + 2);
;     __syncthreads();
.Lg92_tail:
	ds_read_b128 v[204:207], v165 offset:36864
	ds_read_b128 v[172:175], v0
	ds_read_b128 v[212:215], v165 offset:41472
	ds_read_b128 v[180:183], v0 offset:4608
	ds_read_b128 v[188:191], v0 offset:9216
	ds_read_b128 v[196:199], v0 offset:13824
	s_setprio 1
	s_waitcnt lgkmcnt(4)
	v_mfma_f32_32x32x16_bf16 v[114:129], v[204:207], v[172:175], v[114:129]
	ds_read_b128 v[208:211], v165 offset:36896
	s_waitcnt lgkmcnt(4)
	v_mfma_f32_32x32x16_bf16 v[98:113], v[212:215], v[172:175], v[98:113]
	ds_read_b128 v[176:179], v0 offset:32
	ds_read_b128 v[172:175], v0 offset:64
	s_waitcnt lgkmcnt(5)
	v_mfma_f32_32x32x16_bf16 v[82:97], v[204:207], v[180:183], v[82:97]
	ds_read_b128 v[216:219], v165 offset:41504
	v_mfma_f32_32x32x16_bf16 v[66:81], v[212:215], v[180:183], v[66:81]
	ds_read_b128 v[184:187], v0 offset:4640
	ds_read_b128 v[180:183], v0 offset:4672
	s_waitcnt lgkmcnt(7)
	v_mfma_f32_32x32x16_bf16 v[50:65], v[204:207], v[188:191], v[50:65]
	ds_read_b128 v[192:195], v0 offset:9248
	v_mfma_f32_32x32x16_bf16 v[34:49], v[212:215], v[188:191], v[34:49]
	ds_read_b128 v[200:203], v0 offset:13856
	ds_read_b128 v[188:191], v0 offset:9280
	s_waitcnt lgkmcnt(9)
	v_mfma_f32_32x32x16_bf16 v[18:33], v[204:207], v[196:199], v[18:33]
	ds_read_b128 v[204:207], v165 offset:36928
	v_mfma_f32_32x32x16_bf16 v[2:17], v[212:215], v[196:199], v[2:17]
	ds_read_b128 v[212:215], v165 offset:41536
	ds_read_b128 v[196:199], v0 offset:13888
	s_setprio 0
	s_setprio 1
	s_waitcnt lgkmcnt(10)
	v_mfma_f32_32x32x16_bf16 v[114:129], v[208:211], v[176:179], v[114:129]
	s_waitcnt lgkmcnt(8)
	v_mfma_f32_32x32x16_bf16 v[98:113], v[216:219], v[176:179], v[98:113]
	ds_read_b128 v[176:179], v0 offset:96
	s_waitcnt lgkmcnt(8)
	v_mfma_f32_32x32x16_bf16 v[82:97], v[208:211], v[184:187], v[82:97]
	v_mfma_f32_32x32x16_bf16 v[66:81], v[216:219], v[184:187], v[66:81]
	ds_read_b128 v[184:187], v0 offset:4704
	s_waitcnt lgkmcnt(7)
	v_mfma_f32_32x32x16_bf16 v[50:65], v[208:211], v[192:195], v[50:65]
	v_mfma_f32_32x32x16_bf16 v[34:49], v[216:219], v[192:195], v[34:49]
	ds_read_b128 v[192:195], v0 offset:9312
	s_waitcnt lgkmcnt(7)
	v_mfma_f32_32x32x16_bf16 v[18:33], v[208:211], v[200:203], v[18:33]
	ds_read_b128 v[208:211], v165 offset:36960
	v_mfma_f32_32x32x16_bf16 v[2:17], v[216:219], v[200:203], v[2:17]
	ds_read_b128 v[216:219], v165 offset:41568
	ds_read_b128 v[200:203], v0 offset:13920
	s_setprio 0
	s_setprio 1
	s_waitcnt lgkmcnt(8)
	v_mfma_f32_32x32x16_bf16 v[114:129], v[204:207], v[172:175], v[114:129]
	s_waitcnt lgkmcnt(7)
	v_mfma_f32_32x32x16_bf16 v[98:113], v[212:215], v[172:175], v[98:113]
	v_mfma_f32_32x32x16_bf16 v[82:97], v[204:207], v[180:183], v[82:97]
	v_mfma_f32_32x32x16_bf16 v[66:81], v[212:215], v[180:183], v[66:81]
	v_mfma_f32_32x32x16_bf16 v[50:65], v[204:207], v[188:191], v[50:65]
	v_mfma_f32_32x32x16_bf16 v[34:49], v[212:215], v[188:191], v[34:49]
	s_waitcnt lgkmcnt(6)
	v_mfma_f32_32x32x16_bf16 v[18:33], v[204:207], v[196:199], v[18:33]
	v_mfma_f32_32x32x16_bf16 v[2:17], v[212:215], v[196:199], v[2:17]
	s_setprio 0
	s_setprio 1
	s_waitcnt lgkmcnt(2)
	v_mfma_f32_32x32x16_bf16 v[114:129], v[208:211], v[176:179], v[114:129]
	s_waitcnt lgkmcnt(1)
	v_mfma_f32_32x32x16_bf16 v[98:113], v[216:219], v[176:179], v[98:113]
	v_mfma_f32_32x32x16_bf16 v[82:97], v[208:211], v[184:187], v[82:97]
	v_mfma_f32_32x32x16_bf16 v[66:81], v[216:219], v[184:187], v[66:81]
	v_mfma_f32_32x32x16_bf16 v[50:65], v[208:211], v[192:195], v[50:65]
	v_mfma_f32_32x32x16_bf16 v[34:49], v[216:219], v[192:195], v[34:49]
	s_waitcnt lgkmcnt(0)
	v_mfma_f32_32x32x16_bf16 v[18:33], v[208:211], v[200:203], v[18:33]
	v_mfma_f32_32x32x16_bf16 v[2:17], v[216:219], v[200:203], v[2:17]
	s_setprio 0
	s_cmpk_eq_i32 s86, 0xf80
	s_cbranch_scc1 .LBB0_94
	s_and_b32 s62, s53, 2
	s_mul_i32 s62, s62, 0x9000
	v_add_u32_e32 v0, s62, v162
	s_waitcnt vmcnt(7)
	ds_write_b128 v0, v[130:133]
	s_waitcnt vmcnt(6)
	ds_write_b128 v0, v[134:137] offset:36864
	s_waitcnt vmcnt(5)
	ds_write_b128 v0, v[138:141] offset:9216
	s_waitcnt vmcnt(4)
	ds_write_b128 v0, v[142:145] offset:46080
	s_waitcnt vmcnt(3)
	ds_write_b128 v0, v[146:149] offset:18432
	s_waitcnt vmcnt(2)
	ds_write_b128 v0, v[150:153] offset:55296
	s_waitcnt vmcnt(1)
	ds_write_b128 v0, v[154:157] offset:27648
	s_waitcnt vmcnt(0)
	ds_write_b128 v0, v[158:161] offset:64512

; #define MFMA32(a, b, c) __builtin_amdgcn_mfma_f32_32x32x16_bf16((a), (b), (c), 0, 0, 0)
; #define G_LOAD(KT) do { const int k0_ = (KT) << 6; _Pragma("unroll") for (int p = 0; p < 4; ++p) { \
;     ra[p] = *(const u32x4*)(ap + (size_t)(64 * p) * lda + k0_); rb[p] = *(const u32x4*)(bp + (size_t)(64 * p) * ldb + k0_); } } while (0)
; template <bool SWAP, bool SSQ, bool ZERO = true>
; DI void gemm_main(const u16* __restrict__ A, int lda, const u16* __restrict__ Bt, int ldb, int K, char* lds,
;                   f32x16 (&acc)[4][2], float* rs_lds) {
;     ...
;   for (int kt = 0; kt < nk; ++kt) {
;     const int st = (kt & 1) * 2 * G_TILE;
;     {
;       bf16x8 fa[2][4], fb[2][2];
; #pragma unroll
;       for (int i = 0; i < 4; ++i) fa[0][i] = *(const bf16x8*)(abase + st + i * 32 * GS);
; #pragma unroll
;       for (int i = 0; i < 2; ++i) fb[0][i] = *(const bf16x8*)(bbase + st + i * 32 * GS);
; #pragma unroll
;       for (int ks = 0; ks < 4; ++ks) {
;         if (ks + 1 < 4) {
; #pragma unroll
;           for (int i = 0; i < 4; ++i) fa[(ks + 1) & 1][i] = *(const bf16x8*)(abase + st + i * 32 * GS + (ks + 1) * 32);
; #pragma unroll
;           for (int i = 0; i < 2; ++i) fb[(ks + 1) & 1][i] = *(const bf16x8*)(bbase + st + i * 32 * GS + (ks + 1) * 32);
;         }
;         __builtin_amdgcn_sched_barrier(0);
;         __builtin_amdgcn_s_setprio(1);
; #pragma unroll
;         for (int mt = 0; mt < 4; ++mt)
; #pragma unroll
;           for (int nt = 0; nt < 2; ++nt)
;             acc[mt][nt] = SWAP ? MFMA32(fb[ks & 1][nt], fa[ks & 1][mt], acc[mt][nt]) : MFMA32(fa[ks & 1][mt], fb[ks & 1][nt], acc[mt][nt]);
;         __builtin_amdgcn_s_setprio(0);
;         __builtin_amdgcn_sched_barrier(0);
;       }
;     }
;     if (kt + 1 < nk) G_WRITE((kt + 1) & 1);
;     if (kt + 2 < nk) G_LOAD(kt + 2);
;     __syncthreads();
;   }
.LBB0_119:
	s_cmp_gt_u32 s2, 29
	s_cbranch_scc1 .Lg119_tail
	ds_read_b128 v[170:173], v0
	ds_read_b128 v[202:205], v165 offset:36864
	ds_read_b128 v[210:213], v165 offset:41472
	ds_read_b128 v[178:181], v0 offset:4608
	ds_read_b128 v[186:189], v0 offset:9216
	ds_read_b128 v[194:197], v0 offset:13824
	s_setprio 1
	s_waitcnt lgkmcnt(4)
	v_mfma_f32_32x32x16_bf16 v[114:129], v[170:173], v[202:205], v[114:129]
	ds_read_b128 v[174:177], v0 offset:32
	s_waitcnt lgkmcnt(4)
	v_mfma_f32_32x32x16_bf16 v[98:113], v[170:173], v[210:213], v[98:113]
	ds_read_b128 v[206:209], v165 offset:36896
	ds_read_b128 v[170:173], v0 offset:64
	s_waitcnt lgkmcnt(5)
	v_mfma_f32_32x32x16_bf16 v[82:97], v[178:181], v[202:205], v[82:97]
	ds_read_b128 v[214:217], v165 offset:41504
	v_mfma_f32_32x32x16_bf16 v[66:81], v[178:181], v[210:213], v[66:81]
	ds_read_b128 v[182:185], v0 offset:4640
	ds_read_b128 v[178:181], v0 offset:4672
	s_waitcnt lgkmcnt(7)
	v_mfma_f32_32x32x16_bf16 v[50:65], v[186:189], v[202:205], v[50:65]
	ds_read_b128 v[190:193], v0 offset:9248
	v_mfma_f32_32x32x16_bf16 v[34:49], v[186:189], v[210:213], v[34:49]
	ds_read_b128 v[198:201], v0 offset:13856
	ds_read_b128 v[186:189], v0 offset:9280
	s_waitcnt lgkmcnt(9)
	v_mfma_f32_32x32x16_bf16 v[18:33], v[194:197], v[202:205], v[18:33]
	ds_read_b128 v[202:205], v165 offset:36928
	v_mfma_f32_32x32x16_bf16 v[2:17], v[194:197], v[210:213], v[2:17]
	ds_read_b128 v[210:213], v165 offset:41536
	ds_read_b128 v[194:197], v0 offset:13888
	s_setprio 0
	s_setprio 1
	s_waitcnt lgkmcnt(10)
	v_mfma_f32_32x32x16_bf16 v[114:129], v[174:177], v[206:209], v[114:129]
	s_waitcnt lgkmcnt(8)
	v_mfma_f32_32x32x16_bf16 v[98:113], v[174:177], v[214:217], v[98:113]
	ds_read_b128 v[174:177], v0 offset:96
	s_waitcnt lgkmcnt(8)
	v_mfma_f32_32x32x16_bf16 v[82:97], v[182:185], v[206:209], v[82:97]
	v_mfma_f32_32x32x16_bf16 v[66:81], v[182:185], v[214:217], v[66:81]
	ds_read_b128 v[182:185], v0 offset:4704
	s_waitcnt lgkmcnt(7)
	v_mfma_f32_32x32x16_bf16 v[50:65], v[190:193], v[206:209], v[50:65]
	v_mfma_f32_32x32x16_bf16 v[34:49], v[190:193], v[214:217], v[34:49]
	ds_read_b128 v[190:193], v0 offset:9312
	s_waitcnt lgkmcnt(7)
	v_mfma_f32_32x32x16_bf16 v[18:33], v[198:201], v[206:209], v[18:33]
	ds_read_b128 v[206:209], v165 offset:36960
	v_mfma_f32_32x32x16_bf16 v[2:17], v[198:201], v[214:217], v[2:17]
	ds_read_b128 v[214:217], v165 offset:41568
	ds_read_b128 v[198:201], v0 offset:13920
	s_setprio 0
	s_setprio 1
	s_waitcnt lgkmcnt(8)
	v_mfma_f32_32x32x16_bf16 v[114:129], v[170:173], v[202:205], v[114:129]
	s_waitcnt lgkmcnt(7)
	v_mfma_f32_32x32x16_bf16 v[98:113], v[170:173], v[210:213], v[98:113]
	v_mfma_f32_32x32x16_bf16 v[82:97], v[178:181], v[202:205], v[82:97]
	v_mfma_f32_32x32x16_bf16 v[66:81], v[178:181], v[210:213], v[66:81]
	s_and_b32 s52, s4, 2
	s_mul_i32 s52, s52, 0x9000
	v_add_u32_e32 v240, s52, v162
	v_lshl_add_u64 v[220:221], v[168:169], 0, s[0:1]
	v_lshl_add_u64 v[234:235], v[166:167], 0, s[0:1]
	v_mfma_f32_32x32x16_bf16 v[50:65], v[186:189], v[202:205], v[50:65]
	s_waitcnt vmcnt(7)
	ds_write_b128 v240, v[130:133]
	global_load_dwordx4 v[130:133], v[220:221], off offset:256
	v_add_co_u32_e32 v220, vcc, 0x40000, v220
	v_mfma_f32_32x32x16_bf16 v[34:49], v[186:189], v[210:213], v[34:49]
	s_waitcnt vmcnt(7)
	ds_write_b128 v240, v[134:137] offset:36864
	v_addc_co_u32_e32 v221, vcc, 0, v221, vcc
	global_load_dwordx4 v[134:137], v[234:235], off offset:256
	v_add_co_u32_e32 v234, vcc, 0x40000, v234
	s_waitcnt lgkmcnt(8)
	v_mfma_f32_32x32x16_bf16 v[18:33], v[194:197], v[202:205], v[18:33]
	s_waitcnt vmcnt(7)
	ds_write_b128 v240, v[138:141] offset:9216
	v_addc_co_u32_e32 v235, vcc, 0, v235, vcc
	global_load_dwordx4 v[138:141], v[220:221], off offset:256
	v_add_co_u32_e32 v220, vcc, 0x40000, v220
	v_mfma_f32_32x32x16_bf16 v[2:17], v[194:197], v[210:213], v[2:17]
	s_waitcnt vmcnt(7)
	ds_write_b128 v240, v[142:145] offset:46080
	v_addc_co_u32_e32 v221, vcc, 0, v221, vcc
	global_load_dwordx4 v[142:145], v[234:235], off offset:256
	v_add_co_u32_e32 v234, vcc, 0x40000, v234
	s_setprio 0
	s_setprio 1
	s_waitcnt lgkmcnt(6)
	v_mfma_f32_32x32x16_bf16 v[114:129], v[174:177], v[206:209], v[114:129]
	s_waitcnt vmcnt(7)
	ds_write_b128 v240, v[146:149] offset:18432
	v_addc_co_u32_e32 v235, vcc, 0, v235, vcc
	global_load_dwordx4 v[146:149], v[220:221], off offset:256
	v_add_co_u32_e32 v220, vcc, 0x40000, v220
	s_waitcnt lgkmcnt(6)
	v_mfma_f32_32x32x16_bf16 v[98:113], v[174:177], v[214:217], v[98:113]
	s_waitcnt vmcnt(7)
	ds_write_b128 v240, v[150:153] offset:55296
	v_addc_co_u32_e32 v221, vcc, 0, v221, vcc
	global_load_dwordx4 v[150:153], v[234:235], off offset:256
	v_add_co_u32_e32 v234, vcc, 0x40000, v234
	v_mfma_f32_32x32x16_bf16 v[82:97], v[182:185], v[206:209], v[82:97]
	s_waitcnt vmcnt(7)
	ds_write_b128 v240, v[154:157] offset:27648
	v_addc_co_u32_e32 v235, vcc, 0, v235, vcc
	global_load_dwordx4 v[154:157], v[220:221], off offset:256
	v_mfma_f32_32x32x16_bf16 v[66:81], v[182:185], v[214:217], v[66:81]
	s_waitcnt vmcnt(7)
	ds_write_b128 v240, v[158:161] offset:64512
	global_load_dwordx4 v[158:161], v[234:235], off offset:256
	v_mfma_f32_32x32x16_bf16 v[50:65], v[190:193], v[206:209], v[50:65]
	v_mfma_f32_32x32x16_bf16 v[34:49], v[190:193], v[214:217], v[34:49]
	s_waitcnt lgkmcnt(8)
	v_mfma_f32_32x32x16_bf16 v[18:33], v[198:201], v[206:209], v[18:33]
	v_mfma_f32_32x32x16_bf16 v[2:17], v[198:201], v[214:217], v[2:17]
	s_setprio 0
	s_branch .LBB0_118
; #define MFMA32(a, b, c) __builtin_amdgcn_mfma_f32_32x32x16_bf16((a), (b), (c), 0, 0, 0)
; #define G_LOAD(KT) do { const int k0_ = (KT) << 6; _Pragma("unroll") for (int p = 0; p < 4; ++p) { \
;     ra[p] = *(const u32x4*)(ap + (size_t)(64 * p) * lda + k0_); rb[p] = *(const u32x4*)(bp + (size_t)(64 * p) * ldb + k0_); } } while (0)
; template <bool SWAP, bool SSQ, bool ZERO = true>
; DI void gemm_main(const u16* __restrict__ A, int lda, const u16* __restrict__ Bt, int ldb, int K, char* lds,
;                   f32x16 (&acc)[4][2], float* rs_lds) {
;     ...
;   for (int kt = 0; kt < nk; ++kt) {
;     const int st = (kt & 1) * 2 * G_TILE;
;     {
;       bf16x8 fa[2][4], fb[2][2];
; #pragma unroll
;       for (int i = 0; i < 4; ++i) fa[0][i] = *(const bf16x8*)(abase + st + i * 32 * GS);
; #pragma unroll
;       for (int i = 0; i < 2; ++i) fb[0][i] = *(const bf16x8*)(bbase + st + i * 32 * GS);
; #pragma unroll
;       for (int ks = 0; ks < 4; ++ks) {
;         if (ks + 1 < 4) {
; #pragma unroll
;           for (int i = 0; i < 4; ++i) fa[(ks + 1) & 1][i] = *(const bf16x8*)(abase + st + i * 32 * GS + (ks + 1) * 32);
; #pragma unroll
;           for (int i = 0; i < 2; ++i) fb[(ks + 1) & 1][i] = *(const bf16x8*)(bbase + st + i * 32 * GS + (ks + 1) * 32);
;         }
;         __builtin_amdgcn_sched_barrier(0);
;         __builtin_amdgcn_s_setprio(1);
; #pragma unroll
;         for (int mt = 0; mt < 4; ++mt)
; #pragma unroll
;           for (int nt = 0; nt < 2; ++nt)
;             acc[mt][nt] = SWAP ? MFMA32(fb[ks & 1][nt], fa[ks & 1][mt], acc[mt][nt]) : MFMA32(fa[ks & 1][mt], fb[ks & 1][nt], acc[mt][nt]);
;         __builtin_amdgcn_s_setprio(0);
;         __builtin_amdgcn_sched_barrier(0);
;       }
;     }
;     if (kt + 1 < nk) G_WRITE((kt + 1) & 1);
;     if (kt + 2 < nk) G_LOAD(kt + 2);
;     __syncthreads();
.Lg119_tail:
	ds_read_b128 v[170:173], v0
	ds_read_b128 v[202:205], v165 offset:36864
	ds_read_b128 v[210:213], v165 offset:41472
	ds_read_b128 v[178:181], v0 offset:4608
	ds_read_b128 v[186:189], v0 offset:9216
	ds_read_b128 v[194:197], v0 offset:13824
	s_setprio 1
	s_waitcnt lgkmcnt(4)
	v_mfma_f32_32x32x16_bf16 v[114:129], v[170:173], v[202:205], v[114:129]
	ds_read_b128 v[174:177], v0 offset:32
	s_waitcnt lgkmcnt(4)
	v_mfma_f32_32x32x16_bf16 v[98:113], v[170:173], v[210:213], v[98:113]
	ds_read_b128 v[206:209], v165 offset:36896
	ds_read_b128 v[170:173], v0 offset:64
	s_waitcnt lgkmcnt(5)
	v_mfma_f32_32x32x16_bf16 v[82:97], v[178:181], v[202:205], v[82:97]
	ds_read_b128 v[214:217], v165 offset:41504
	v_mfma_f32_32x32x16_bf16 v[66:81], v[178:181], v[210:213], v[66:81]
	ds_read_b128 v[182:185], v0 offset:4640
	ds_read_b128 v[178:181], v0 offset:4672
	s_waitcnt lgkmcnt(7)
	v_mfma_f32_32x32x16_bf16 v[50:65], v[186:189], v[202:205], v[50:65]
	ds_read_b128 v[190:193], v0 offset:9248
	v_mfma_f32_32x32x16_bf16 v[34:49], v[186:189], v[210:213], v[34:49]
	ds_read_b128 v[198:201], v0 offset:13856
	ds_read_b128 v[186:189], v0 offset:9280
	s_waitcnt lgkmcnt(9)
	v_mfma_f32_32x32x16_bf16 v[18:33], v[194:197], v[202:205], v[18:33]
	ds_read_b128 v[202:205], v165 offset:36928
	v_mfma_f32_32x32x16_bf16 v[2:17], v[194:197], v[210:213], v[2:17]
	ds_read_b128 v[210:213], v165 offset:41536
	ds_read_b128 v[194:197], v0 offset:13888
	s_setprio 0
	s_setprio 1
	s_waitcnt lgkmcnt(10)
	v_mfma_f32_32x32x16_bf16 v[114:129], v[174:177], v[206:209], v[114:129]
	s_waitcnt lgkmcnt(8)
	v_mfma_f32_32x32x16_bf16 v[98:113], v[174:177], v[214:217], v[98:113]
	ds_read_b128 v[174:177], v0 offset:96
	s_waitcnt lgkmcnt(8)
	v_mfma_f32_32x32x16_bf16 v[82:97], v[182:185], v[206:209], v[82:97]
	v_mfma_f32_32x32x16_bf16 v[66:81], v[182:185], v[214:217], v[66:81]
	ds_read_b128 v[182:185], v0 offset:4704
	s_waitcnt lgkmcnt(7)
	v_mfma_f32_32x32x16_bf16 v[50:65], v[190:193], v[206:209], v[50:65]
	v_mfma_f32_32x32x16_bf16 v[34:49], v[190:193], v[214:217], v[34:49]
	ds_read_b128 v[190:193], v0 offset:9312
	s_waitcnt lgkmcnt(7)
	v_mfma_f32_32x32x16_bf16 v[18:33], v[198:201], v[206:209], v[18:33]
	ds_read_b128 v[206:209], v165 offset:36960
	v_mfma_f32_32x32x16_bf16 v[2:17], v[198:201], v[214:217], v[2:17]
	ds_read_b128 v[214:217], v165 offset:41568
	ds_read_b128 v[198:201], v0 offset:13920
	s_setprio 0
	s_setprio 1
	s_waitcnt lgkmcnt(8)
	v_mfma_f32_32x32x16_bf16 v[114:129], v[170:173], v[202:205], v[114:129]
	s_waitcnt lgkmcnt(7)
	v_mfma_f32_32x32x16_bf16 v[98:113], v[170:173], v[210:213], v[98:113]
	v_mfma_f32_32x32x16_bf16 v[82:97], v[178:181], v[202:205], v[82:97]
	v_mfma_f32_32x32x16_bf16 v[66:81], v[178:181], v[210:213], v[66:81]
	v_mfma_f32_32x32x16_bf16 v[50:65], v[186:189], v[202:205], v[50:65]
	v_mfma_f32_32x32x16_bf16 v[34:49], v[186:189], v[210:213], v[34:49]
	s_waitcnt lgkmcnt(6)
	v_mfma_f32_32x32x16_bf16 v[18:33], v[194:197], v[202:205], v[18:33]
	v_mfma_f32_32x32x16_bf16 v[2:17], v[194:197], v[210:213], v[2:17]
	s_setprio 0
	s_setprio 1
	s_waitcnt lgkmcnt(2)
	v_mfma_f32_32x32x16_bf16 v[114:129], v[174:177], v[206:209], v[114:129]
	s_waitcnt lgkmcnt(1)
	v_mfma_f32_32x32x16_bf16 v[98:113], v[174:177], v[214:217], v[98:113]
	v_mfma_f32_32x32x16_bf16 v[82:97], v[182:185], v[206:209], v[82:97]
	v_mfma_f32_32x32x16_bf16 v[66:81], v[182:185], v[214:217], v[66:81]
	v_mfma_f32_32x32x16_bf16 v[50:65], v[190:193], v[206:209], v[50:65]
	v_mfma_f32_32x32x16_bf16 v[34:49], v[190:193], v[214:217], v[34:49]
	s_waitcnt lgkmcnt(0)
	v_mfma_f32_32x32x16_bf16 v[18:33], v[198:201], v[206:209], v[18:33]
	v_mfma_f32_32x32x16_bf16 v[2:17], v[198:201], v[214:217], v[2:17]
	s_setprio 0
	s_cmpk_eq_i32 s0, 0xf80
	s_cbranch_scc1 .LBB0_121
	s_and_b32 s52, s4, 2
	s_mul_i32 s52, s52, 0x9000
	v_add_u32_e32 v0, s52, v162
	s_waitcnt vmcnt(7)
	ds_write_b128 v0, v[130:133]
	s_waitcnt vmcnt(6)
	ds_write_b128 v0, v[134:137] offset:36864
	s_waitcnt vmcnt(5)
	ds_write_b128 v0, v[138:141] offset:9216
	s_waitcnt vmcnt(4)
	ds_write_b128 v0, v[142:145] offset:46080
	s_waitcnt vmcnt(3)
	ds_write_b128 v0, v[146:149] offset:18432
	s_waitcnt vmcnt(2)
	ds_write_b128 v0, v[150:153] offset:55296
	s_waitcnt vmcnt(1)
	ds_write_b128 v0, v[154:157] offset:27648
	s_waitcnt vmcnt(0)
	ds_write_b128 v0, v[158:161] offset:64512

; #define MFMA32(a, b, c) __builtin_amdgcn_mfma_f32_32x32x16_bf16((a), (b), (c), 0, 0, 0)
; #define G_LOAD(KT) do { const int k0_ = (KT) << 6; _Pragma("unroll") for (int p = 0; p < 4; ++p) { \
;     ra[p] = *(const u32x4*)(ap + (size_t)(64 * p) * lda + k0_); rb[p] = *(const u32x4*)(bp + (size_t)(64 * p) * ldb + k0_); } } while (0)
; template <bool SWAP, bool SSQ, bool ZERO = true>
; DI void gemm_main(const u16* __restrict__ A, int lda, const u16* __restrict__ Bt, int ldb, int K, char* lds,
;                   f32x16 (&acc)[4][2], float* rs_lds) {
;     ...
;   for (int kt = 0; kt < nk; ++kt) {
;     const int st = (kt & 1) * 2 * G_TILE;
;     {
;       bf16x8 fa[2][4], fb[2][2];
; #pragma unroll
;       for (int i = 0; i < 4; ++i) fa[0][i] = *(const bf16x8*)(abase + st + i * 32 * GS);
; #pragma unroll
;       for (int i = 0; i < 2; ++i) fb[0][i] = *(const bf16x8*)(bbase + st + i * 32 * GS);
; #pragma unroll
;       for (int ks = 0; ks < 4; ++ks) {
;         if (ks + 1 < 4) {
; #pragma unroll
;           for (int i = 0; i < 4; ++i) fa[(ks + 1) & 1][i] = *(const bf16x8*)(abase + st + i * 32 * GS + (ks + 1) * 32);
; #pragma unroll
;           for (int i = 0; i < 2; ++i) fb[(ks + 1) & 1][i] = *(const bf16x8*)(bbase + st + i * 32 * GS + (ks + 1) * 32);
;         }
;         __builtin_amdgcn_sched_barrier(0);
;         __builtin_amdgcn_s_setprio(1);
; #pragma unroll
;         for (int mt = 0; mt < 4; ++mt)
; #pragma unroll
;           for (int nt = 0; nt < 2; ++nt)
;             acc[mt][nt] = SWAP ? MFMA32(fb[ks & 1][nt], fa[ks & 1][mt], acc[mt][nt]) : MFMA32(fa[ks & 1][mt], fb[ks & 1][nt], acc[mt][nt]);
;         __builtin_amdgcn_s_setprio(0);
;         __builtin_amdgcn_sched_barrier(0);
;       }
;     }
;     if (kt + 1 < nk) G_WRITE((kt + 1) & 1);
;     if (kt + 2 < nk) G_LOAD(kt + 2);
;     __syncthreads();
;   }
.LBB0_292:
	s_cmp_gt_u32 s86, 29
	s_cbranch_scc1 .Lg292_tail
	ds_read_b128 v[214:217], v240 offset:36864
	ds_read_b128 v[182:185], v177
	ds_read_b128 v[232:235], v240 offset:41472
	ds_read_b128 v[190:193], v177 offset:4608
	ds_read_b128 v[198:201], v177 offset:9216
	ds_read_b128 v[206:209], v177 offset:13824
	s_setprio 1
	s_waitcnt lgkmcnt(4)
	v_mfma_f32_32x32x16_bf16 v[114:129], v[214:217], v[182:185], v[114:129]
	ds_read_b128 v[218:221], v240 offset:36896
	s_waitcnt lgkmcnt(4)
	v_mfma_f32_32x32x16_bf16 v[98:113], v[232:235], v[182:185], v[98:113]
	ds_read_b128 v[186:189], v177 offset:32
	ds_read_b128 v[182:185], v177 offset:64
	s_waitcnt lgkmcnt(5)
	v_mfma_f32_32x32x16_bf16 v[82:97], v[214:217], v[190:193], v[82:97]
	ds_read_b128 v[236:239], v240 offset:41504
	v_mfma_f32_32x32x16_bf16 v[66:81], v[232:235], v[190:193], v[66:81]
	ds_read_b128 v[194:197], v177 offset:4640
	ds_read_b128 v[190:193], v177 offset:4672
	s_waitcnt lgkmcnt(7)
	v_mfma_f32_32x32x16_bf16 v[50:65], v[214:217], v[198:201], v[50:65]
	ds_read_b128 v[202:205], v177 offset:9248
	v_mfma_f32_32x32x16_bf16 v[34:49], v[232:235], v[198:201], v[34:49]
	ds_read_b128 v[210:213], v177 offset:13856
	ds_read_b128 v[198:201], v177 offset:9280
	s_waitcnt lgkmcnt(9)
	v_mfma_f32_32x32x16_bf16 v[18:33], v[214:217], v[206:209], v[18:33]
	ds_read_b128 v[214:217], v240 offset:36928
	v_mfma_f32_32x32x16_bf16 v[2:17], v[232:235], v[206:209], v[2:17]
	ds_read_b128 v[232:235], v240 offset:41536
	ds_read_b128 v[206:209], v177 offset:13888
	s_setprio 0
	s_setprio 1
	s_waitcnt lgkmcnt(10)
	v_mfma_f32_32x32x16_bf16 v[114:129], v[218:221], v[186:189], v[114:129]
	s_waitcnt lgkmcnt(8)
	v_mfma_f32_32x32x16_bf16 v[98:113], v[236:239], v[186:189], v[98:113]
	ds_read_b128 v[186:189], v177 offset:96
	s_waitcnt lgkmcnt(8)
	v_mfma_f32_32x32x16_bf16 v[82:97], v[218:221], v[194:197], v[82:97]
	v_mfma_f32_32x32x16_bf16 v[66:81], v[236:239], v[194:197], v[66:81]
	ds_read_b128 v[194:197], v177 offset:4704
	s_waitcnt lgkmcnt(7)
	v_mfma_f32_32x32x16_bf16 v[50:65], v[218:221], v[202:205], v[50:65]
	v_mfma_f32_32x32x16_bf16 v[34:49], v[236:239], v[202:205], v[34:49]
	ds_read_b128 v[202:205], v177 offset:9312
	s_waitcnt lgkmcnt(7)
	v_mfma_f32_32x32x16_bf16 v[18:33], v[218:221], v[210:213], v[18:33]
	ds_read_b128 v[218:221], v240 offset:36960
	v_mfma_f32_32x32x16_bf16 v[2:17], v[236:239], v[210:213], v[2:17]
	ds_read_b128 v[236:239], v240 offset:41568
	ds_read_b128 v[210:213], v177 offset:13920
	s_setprio 0
	s_setprio 1
	s_waitcnt lgkmcnt(8)
	v_mfma_f32_32x32x16_bf16 v[114:129], v[214:217], v[182:185], v[114:129]
	s_waitcnt lgkmcnt(7)
	v_mfma_f32_32x32x16_bf16 v[98:113], v[232:235], v[182:185], v[98:113]
	v_mfma_f32_32x32x16_bf16 v[82:97], v[214:217], v[190:193], v[82:97]
	v_mfma_f32_32x32x16_bf16 v[66:81], v[232:235], v[190:193], v[66:81]
	s_and_b32 s4, s85, 2
	s_mul_i32 s4, s4, 0x9000
	v_add_u32_e32 v242, s4, v174
	v_lshl_add_u64 v[244:245], v[180:181], 0, s[82:83]
	v_lshl_add_u64 v[246:247], v[178:179], 0, s[82:83]
	v_mfma_f32_32x32x16_bf16 v[50:65], v[214:217], v[198:201], v[50:65]
	s_waitcnt vmcnt(7)
	ds_write_b128 v242, v[130:133]
	global_load_dwordx4 v[130:133], v[244:245], off offset:256
	v_add_co_u32_e32 v244, vcc, 0x40000, v244
	v_mfma_f32_32x32x16_bf16 v[34:49], v[232:235], v[198:201], v[34:49]
	s_waitcnt vmcnt(7)
	ds_write_b128 v242, v[134:137] offset:36864
	v_addc_co_u32_e32 v245, vcc, 0, v245, vcc
	global_load_dwordx4 v[134:137], v[246:247], off offset:256
	v_add_co_u32_e32 v246, vcc, 0x40000, v246
	s_waitcnt lgkmcnt(8)
	v_mfma_f32_32x32x16_bf16 v[18:33], v[214:217], v[206:209], v[18:33]
	s_waitcnt vmcnt(7)
	ds_write_b128 v242, v[138:141] offset:9216
	v_addc_co_u32_e32 v247, vcc, 0, v247, vcc
	global_load_dwordx4 v[138:141], v[244:245], off offset:256
	v_add_co_u32_e32 v244, vcc, 0x40000, v244
	v_mfma_f32_32x32x16_bf16 v[2:17], v[232:235], v[206:209], v[2:17]
	s_waitcnt vmcnt(7)
	ds_write_b128 v242, v[142:145] offset:46080
	v_addc_co_u32_e32 v245, vcc, 0, v245, vcc
	global_load_dwordx4 v[142:145], v[246:247], off offset:256
	v_add_co_u32_e32 v246, vcc, 0x40000, v246
	s_setprio 0
	s_setprio 1
	s_waitcnt lgkmcnt(6)
	v_mfma_f32_32x32x16_bf16 v[114:129], v[218:221], v[186:189], v[114:129]
	s_waitcnt vmcnt(7)
	ds_write_b128 v242, v[146:149] offset:18432
	v_addc_co_u32_e32 v247, vcc, 0, v247, vcc
	global_load_dwordx4 v[146:149], v[244:245], off offset:256
	v_add_co_u32_e32 v244, vcc, 0x40000, v244
	s_waitcnt lgkmcnt(6)
	v_mfma_f32_32x32x16_bf16 v[98:113], v[236:239], v[186:189], v[98:113]
	s_waitcnt vmcnt(7)
	ds_write_b128 v242, v[150:153] offset:55296
	v_addc_co_u32_e32 v245, vcc, 0, v245, vcc
	global_load_dwordx4 v[150:153], v[246:247], off offset:256
	v_add_co_u32_e32 v246, vcc, 0x40000, v246
	v_mfma_f32_32x32x16_bf16 v[82:97], v[218:221], v[194:197], v[82:97]
	s_waitcnt vmcnt(7)
	ds_write_b128 v242, v[154:157] offset:27648
	v_addc_co_u32_e32 v247, vcc, 0, v247, vcc
	global_load_dwordx4 v[154:157], v[244:245], off offset:256
	v_mfma_f32_32x32x16_bf16 v[66:81], v[236:239], v[194:197], v[66:81]
	s_waitcnt vmcnt(7)
	ds_write_b128 v242, v[158:161] offset:64512
	global_load_dwordx4 v[158:161], v[246:247], off offset:256
	v_mfma_f32_32x32x16_bf16 v[50:65], v[218:221], v[202:205], v[50:65]
	v_mfma_f32_32x32x16_bf16 v[34:49], v[236:239], v[202:205], v[34:49]
	s_waitcnt lgkmcnt(8)
	v_mfma_f32_32x32x16_bf16 v[18:33], v[218:221], v[210:213], v[18:33]
	v_mfma_f32_32x32x16_bf16 v[2:17], v[236:239], v[210:213], v[2:17]
	s_setprio 0
	s_branch .LBB0_291
; #define MFMA32(a, b, c) __builtin_amdgcn_mfma_f32_32x32x16_bf16((a), (b), (c), 0, 0, 0)
; #define G_LOAD(KT) do { const int k0_ = (KT) << 6; _Pragma("unroll") for (int p = 0; p < 4; ++p) { \
;     ra[p] = *(const u32x4*)(ap + (size_t)(64 * p) * lda + k0_); rb[p] = *(const u32x4*)(bp + (size_t)(64 * p) * ldb + k0_); } } while (0)
; template <bool SWAP, bool SSQ, bool ZERO = true>
; DI void gemm_main(const u16* __restrict__ A, int lda, const u16* __restrict__ Bt, int ldb, int K, char* lds,
;                   f32x16 (&acc)[4][2], float* rs_lds) {
;     ...
;   for (int kt = 0; kt < nk; ++kt) {
;     const int st = (kt & 1) * 2 * G_TILE;
;     {
;       bf16x8 fa[2][4], fb[2][2];
; #pragma unroll
;       for (int i = 0; i < 4; ++i) fa[0][i] = *(const bf16x8*)(abase + st + i * 32 * GS);
; #pragma unroll
;       for (int i = 0; i < 2; ++i) fb[0][i] = *(const bf16x8*)(bbase + st + i * 32 * GS);
; #pragma unroll
;       for (int ks = 0; ks < 4; ++ks) {
;         if (ks + 1 < 4) {
; #pragma unroll
;           for (int i = 0; i < 4; ++i) fa[(ks + 1) & 1][i] = *(const bf16x8*)(abase + st + i * 32 * GS + (ks + 1) * 32);
; #pragma unroll
;           for (int i = 0; i < 2; ++i) fb[(ks + 1) & 1][i] = *(const bf16x8*)(bbase + st + i * 32 * GS + (ks + 1) * 32);
;         }
;         __builtin_amdgcn_sched_barrier(0);
;         __builtin_amdgcn_s_setprio(1);
; #pragma unroll
;         for (int mt = 0; mt < 4; ++mt)
; #pragma unroll
;           for (int nt = 0; nt < 2; ++nt)
;             acc[mt][nt] = SWAP ? MFMA32(fb[ks & 1][nt], fa[ks & 1][mt], acc[mt][nt]) : MFMA32(fa[ks & 1][mt], fb[ks & 1][nt], acc[mt][nt]);
;         __builtin_amdgcn_s_setprio(0);
;         __builtin_amdgcn_sched_barrier(0);
;       }
;     }
;     if (kt + 1 < nk) G_WRITE((kt + 1) & 1);
;     if (kt + 2 < nk) G_LOAD(kt + 2);
;     __syncthreads();
;   }
.Lg292_tail:
	ds_read_b128 v[214:217], v240 offset:36864
	ds_read_b128 v[182:185], v177
	ds_read_b128 v[232:235], v240 offset:41472
	ds_read_b128 v[190:193], v177 offset:4608
	ds_read_b128 v[198:201], v177 offset:9216
	ds_read_b128 v[206:209], v177 offset:13824
	s_setprio 1
	s_waitcnt lgkmcnt(4)
	v_mfma_f32_32x32x16_bf16 v[114:129], v[214:217], v[182:185], v[114:129]
	ds_read_b128 v[218:221], v240 offset:36896
	s_waitcnt lgkmcnt(4)
	v_mfma_f32_32x32x16_bf16 v[98:113], v[232:235], v[182:185], v[98:113]
	ds_read_b128 v[186:189], v177 offset:32
	ds_read_b128 v[182:185], v177 offset:64
	s_waitcnt lgkmcnt(5)
	v_mfma_f32_32x32x16_bf16 v[82:97], v[214:217], v[190:193], v[82:97]
	ds_read_b128 v[236:239], v240 offset:41504
	v_mfma_f32_32x32x16_bf16 v[66:81], v[232:235], v[190:193], v[66:81]
	ds_read_b128 v[194:197], v177 offset:4640
	ds_read_b128 v[190:193], v177 offset:4672
	s_waitcnt lgkmcnt(7)
	v_mfma_f32_32x32x16_bf16 v[50:65], v[214:217], v[198:201], v[50:65]
	ds_read_b128 v[202:205], v177 offset:9248
	v_mfma_f32_32x32x16_bf16 v[34:49], v[232:235], v[198:201], v[34:49]
	ds_read_b128 v[210:213], v177 offset:13856
	ds_read_b128 v[198:201], v177 offset:9280
	s_waitcnt lgkmcnt(9)
	v_mfma_f32_32x32x16_bf16 v[18:33], v[214:217], v[206:209], v[18:33]
	ds_read_b128 v[214:217], v240 offset:36928
	v_mfma_f32_32x32x16_bf16 v[2:17], v[232:235], v[206:209], v[2:17]
	ds_read_b128 v[232:235], v240 offset:41536
	ds_read_b128 v[206:209], v177 offset:13888
	s_setprio 0
	s_setprio 1
	s_waitcnt lgkmcnt(10)
	v_mfma_f32_32x32x16_bf16 v[114:129], v[218:221], v[186:189], v[114:129]
	s_waitcnt lgkmcnt(8)
	v_mfma_f32_32x32x16_bf16 v[98:113], v[236:239], v[186:189], v[98:113]
	ds_read_b128 v[186:189], v177 offset:96
	s_waitcnt lgkmcnt(8)
	v_mfma_f32_32x32x16_bf16 v[82:97], v[218:221], v[194:197], v[82:97]
	v_mfma_f32_32x32x16_bf16 v[66:81], v[236:239], v[194:197], v[66:81]
	ds_read_b128 v[194:197], v177 offset:4704
	s_waitcnt lgkmcnt(7)
	v_mfma_f32_32x32x16_bf16 v[50:65], v[218:221], v[202:205], v[50:65]
	v_mfma_f32_32x32x16_bf16 v[34:49], v[236:239], v[202:205], v[34:49]
	ds_read_b128 v[202:205], v177 offset:9312
	s_waitcnt lgkmcnt(7)
	v_mfma_f32_32x32x16_bf16 v[18:33], v[218:221], v[210:213], v[18:33]
	ds_read_b128 v[218:221], v240 offset:36960
	v_mfma_f32_32x32x16_bf16 v[2:17], v[236:239], v[210:213], v[2:17]
	ds_read_b128 v[236:239], v240 offset:41568
	ds_read_b128 v[210:213], v177 offset:13920
	s_setprio 0
	s_setprio 1
	s_waitcnt lgkmcnt(8)
	v_mfma_f32_32x32x16_bf16 v[114:129], v[214:217], v[182:185], v[114:129]
	s_waitcnt lgkmcnt(7)
	v_mfma_f32_32x32x16_bf16 v[98:113], v[232:235], v[182:185], v[98:113]
	v_mfma_f32_32x32x16_bf16 v[82:97], v[214:217], v[190:193], v[82:97]
	v_mfma_f32_32x32x16_bf16 v[66:81], v[232:235], v[190:193], v[66:81]
	v_mfma_f32_32x32x16_bf16 v[50:65], v[214:217], v[198:201], v[50:65]
	v_mfma_f32_32x32x16_bf16 v[34:49], v[232:235], v[198:201], v[34:49]
	s_waitcnt lgkmcnt(6)
	v_mfma_f32_32x32x16_bf16 v[18:33], v[214:217], v[206:209], v[18:33]
	v_mfma_f32_32x32x16_bf16 v[2:17], v[232:235], v[206:209], v[2:17]
	s_setprio 0
	s_setprio 1
	s_waitcnt lgkmcnt(2)
	v_mfma_f32_32x32x16_bf16 v[114:129], v[218:221], v[186:189], v[114:129]
	s_waitcnt lgkmcnt(1)
	v_mfma_f32_32x32x16_bf16 v[98:113], v[236:239], v[186:189], v[98:113]
	v_mfma_f32_32x32x16_bf16 v[82:97], v[218:221], v[194:197], v[82:97]
	v_mfma_f32_32x32x16_bf16 v[66:81], v[236:239], v[194:197], v[66:81]
	v_mfma_f32_32x32x16_bf16 v[50:65], v[218:221], v[202:205], v[50:65]
	v_mfma_f32_32x32x16_bf16 v[34:49], v[236:239], v[202:205], v[34:49]
	s_waitcnt lgkmcnt(0)
	v_mfma_f32_32x32x16_bf16 v[18:33], v[218:221], v[210:213], v[18:33]
	v_mfma_f32_32x32x16_bf16 v[2:17], v[236:239], v[210:213], v[2:17]
	s_setprio 0
	s_cmpk_eq_i32 s82, 0xf80
	s_cbranch_scc1 .LBB0_294
	s_and_b32 s4, s85, 2
	s_mul_i32 s4, s4, 0x9000
	v_add_u32_e32 v177, s4, v174
	s_waitcnt vmcnt(7)
	ds_write_b128 v177, v[130:133]
	s_waitcnt vmcnt(6)
	ds_write_b128 v177, v[134:137] offset:36864
	s_waitcnt vmcnt(5)
	ds_write_b128 v177, v[138:141] offset:9216
	s_waitcnt vmcnt(4)
	ds_write_b128 v177, v[142:145] offset:46080
	s_waitcnt vmcnt(3)
	ds_write_b128 v177, v[146:149] offset:18432
	s_waitcnt vmcnt(2)
	ds_write_b128 v177, v[150:153] offset:55296
	s_waitcnt vmcnt(1)
	ds_write_b128 v177, v[154:157] offset:27648
	s_waitcnt vmcnt(0)
	ds_write_b128 v177, v[158:161] offset:64512
